# v30 + gate/up GEMM: sum-of-squares partials for the RMS scales prefetched at the tile head (counted wait after the K loop instead of 4 exposed loads + vmcnt(0))
# speedup vs baseline: 1.0216x; 1.0013x over previous
.LBB0_145:
	s_bitcmp1_b32 s47, 0
	s_cbranch_scc1 .Lgu_nossq
	s_and_b64 s[100:101], s[12:13], exec
	s_cselect_b32 s100, s22, s49
	v_lshl_or_b32 v242, s100, 8, v145
	v_ashrrev_i32_e32 v243, 31, v242
	v_lshlrev_b64 v[242:243], 6, v[242:243]
	v_lshl_add_u64 v[242:243], s[4:5], 0, v[242:243]
	global_load_dwordx4 v[226:229], v[242:243], off offset:48
	global_load_dwordx4 v[230:233], v[242:243], off offset:32
	global_load_dwordx4 v[234:237], v[242:243], off offset:16
	global_load_dwordx4 v[238:241], v[242:243], off
.Lgu_nossq:

	s_ashr_i32 s17, s16, 31
	s_lshl_b64 s[18:19], s[16:17], 19
	s_add_u32 s18, s36, s18
	s_addc_u32 s19, s37, s19
	s_and_b64 s[20:21], s[2:3], exec
	s_cselect_b32 s17, s19, s25
	s_cselect_b32 s50, s18, s24
	s_ashr_i32 s15, s14, 31
	s_lshl_b64 s[20:21], s[14:15], 19
	s_add_u32 s20, s34, s20
	s_addc_u32 s21, s35, s21
	s_and_b64 s[28:29], s[2:3], exec
	s_cselect_b32 s15, s21, s27
	s_cselect_b32 s51, s20, s26
	s_add_u32 s24, s24, 0x40080
	s_addc_u32 s25, s25, 0
	s_add_u32 s52, s26, 0x100
	v_mov_b32_e32 v0, 0
	s_addc_u32 s53, s27, 0
	s_mov_b32 s54, -2
	v_mov_b32_e32 v1, v0
	v_mov_b32_e32 v2, v0
	v_mov_b32_e32 v3, v0
	v_mov_b32_e32 v8, v0
	v_mov_b32_e32 v9, v0
	v_mov_b32_e32 v10, v0
	v_mov_b32_e32 v11, v0
	v_mov_b32_e32 v16, v0
	v_mov_b32_e32 v17, v0
	v_mov_b32_e32 v18, v0
	v_mov_b32_e32 v19, v0
	v_mov_b32_e32 v24, v0
	v_mov_b32_e32 v25, v0
	v_mov_b32_e32 v26, v0
	v_mov_b32_e32 v27, v0
	v_mov_b32_e32 v32, v0
	v_mov_b32_e32 v33, v0
	v_mov_b32_e32 v34, v0
	v_mov_b32_e32 v35, v0
	v_mov_b32_e32 v40, v0
	v_mov_b32_e32 v41, v0
	v_mov_b32_e32 v42, v0
	v_mov_b32_e32 v43, v0
	v_mov_b32_e32 v48, v0
	v_mov_b32_e32 v49, v0
	v_mov_b32_e32 v50, v0
	v_mov_b32_e32 v51, v0
	v_mov_b32_e32 v56, v0
	v_mov_b32_e32 v57, v0
	v_mov_b32_e32 v58, v0
	v_mov_b32_e32 v59, v0
	v_mov_b32_e32 v4, v0
	v_mov_b32_e32 v5, v0
	v_mov_b32_e32 v6, v0
	v_mov_b32_e32 v7, v0
	v_mov_b32_e32 v12, v0
	v_mov_b32_e32 v13, v0
	v_mov_b32_e32 v14, v0
	v_mov_b32_e32 v15, v0
	v_mov_b32_e32 v20, v0
	v_mov_b32_e32 v21, v0
	v_mov_b32_e32 v22, v0
	v_mov_b32_e32 v23, v0
	v_mov_b32_e32 v28, v0
	v_mov_b32_e32 v29, v0
	v_mov_b32_e32 v30, v0
	v_mov_b32_e32 v31, v0
	v_mov_b32_e32 v36, v0
	v_mov_b32_e32 v37, v0
	v_mov_b32_e32 v38, v0
	v_mov_b32_e32 v39, v0
	v_mov_b32_e32 v44, v0
	v_mov_b32_e32 v45, v0
	v_mov_b32_e32 v46, v0
	v_mov_b32_e32 v47, v0
	v_mov_b32_e32 v52, v0
	v_mov_b32_e32 v53, v0
	v_mov_b32_e32 v54, v0
	v_mov_b32_e32 v55, v0
	v_mov_b32_e32 v60, v0
	v_mov_b32_e32 v61, v0
	v_mov_b32_e32 v62, v0
	v_mov_b32_e32 v63, v0
	v_mov_b32_e32 v64, v0
	v_mov_b32_e32 v65, v0
	v_mov_b32_e32 v66, v0
	v_mov_b32_e32 v67, v0
	v_mov_b32_e32 v72, v0
	v_mov_b32_e32 v73, v0
	v_mov_b32_e32 v74, v0
	v_mov_b32_e32 v75, v0
	v_mov_b32_e32 v80, v0
	v_mov_b32_e32 v81, v0
	v_mov_b32_e32 v82, v0
	v_mov_b32_e32 v83, v0
	v_mov_b32_e32 v88, v0
	v_mov_b32_e32 v89, v0
	v_mov_b32_e32 v90, v0
	v_mov_b32_e32 v91, v0
	v_mov_b32_e32 v98, v0
	v_mov_b32_e32 v99, v0
	v_mov_b32_e32 v100, v0
	v_mov_b32_e32 v101, v0
	v_mov_b32_e32 v106, v0
	v_mov_b32_e32 v107, v0
	v_mov_b32_e32 v108, v0
	v_mov_b32_e32 v109, v0
	v_mov_b32_e32 v114, v0
	v_mov_b32_e32 v115, v0
	v_mov_b32_e32 v116, v0
	v_mov_b32_e32 v117, v0
	v_mov_b32_e32 v122, v0
	v_mov_b32_e32 v123, v0
	v_mov_b32_e32 v124, v0
	v_mov_b32_e32 v125, v0
	v_mov_b32_e32 v68, v0
	v_mov_b32_e32 v69, v0
	v_mov_b32_e32 v70, v0
	v_mov_b32_e32 v71, v0
	v_mov_b32_e32 v76, v0
	v_mov_b32_e32 v77, v0
	v_mov_b32_e32 v78, v0
	v_mov_b32_e32 v79, v0
	v_mov_b32_e32 v84, v0
	v_mov_b32_e32 v85, v0
	v_mov_b32_e32 v86, v0
	v_mov_b32_e32 v87, v0
	v_mov_b32_e32 v92, v0
	v_mov_b32_e32 v93, v0
	v_mov_b32_e32 v94, v0
	v_mov_b32_e32 v95, v0
	v_mov_b32_e32 v102, v0
	v_mov_b32_e32 v103, v0
	v_mov_b32_e32 v104, v0
	v_mov_b32_e32 v105, v0
	v_mov_b32_e32 v110, v0
	v_mov_b32_e32 v111, v0
	v_mov_b32_e32 v112, v0
	v_mov_b32_e32 v113, v0
	v_mov_b32_e32 v118, v0
	v_mov_b32_e32 v119, v0
	v_mov_b32_e32 v120, v0
	v_mov_b32_e32 v121, v0
	v_mov_b32_e32 v126, v0
	v_mov_b32_e32 v127, v0
	v_mov_b32_e32 v128, v0
	v_mov_b32_e32 v129, v0
	s_add_u32 s26, s24, 0xfffc0080
	s_addc_u32 s27, s25, -1
	s_add_i32 s55, 0, 0x10000
	s_cmp_eq_u32 s54, 12
	s_cselect_b32 s29, s17, s27
	s_cselect_b32 s28, s50, s26
	v_add_u32_e32 v140, s55, v143
	s_cselect_b32 s27, s15, s53
	s_cselect_b32 s26, s51, s52
	s_add_i32 s60, 0, 0x14000
	ds_read_b128 v[150:153], v140
	ds_read_b128 v[154:157], v140 offset:1024
	ds_read_b128 v[158:161], v140 offset:2048
	ds_read_b128 v[162:165], v140 offset:3072
	v_add_u32_e32 v140, s60, v143
	ds_read_b128 v[166:169], v140
	ds_read_b128 v[170:173], v140 offset:1024
	ds_read_b128 v[174:177], v140 offset:2048
	ds_read_b128 v[178:181], v140 offset:3072
	v_lshl_add_u64 v[140:141], s[24:25], 0, v[136:137]
	s_add_i32 m0, s40, 0xc000
	ds_read_b128 v[182:185], v148
	ds_read_b128 v[186:189], v148 offset:1024
	ds_read_b128 v[190:193], v148 offset:2048
	ds_read_b128 v[202:205], v148 offset:3072
	ds_read_b128 v[206:209], v148 offset:4096
	ds_read_b128 v[210:213], v148 offset:5120
	ds_read_b128 v[214:217], v148 offset:6144
	ds_read_b128 v[218:221], v148 offset:7168
	global_load_lds_dwordx4 v[140:141], off
	v_lshl_add_u64 v[140:141], s[24:25], 0, v[138:139]
	s_add_i32 m0, s40, 0xe000
	s_nop 0
	global_load_lds_dwordx4 v[140:141], off
	s_waitcnt lgkmcnt(0)
	s_barrier
	s_setprio 1
	s_waitcnt lgkmcnt(0)
	v_mfma_f32_16x16x32_bf16 v[126:129], v[150:153], v[182:185], v[126:129]
	v_mfma_f32_16x16x32_bf16 v[118:121], v[158:161], v[182:185], v[118:121]
	v_mfma_f32_16x16x32_bf16 v[110:113], v[150:153], v[190:193], v[110:113]
	v_mfma_f32_16x16x32_bf16 v[102:105], v[158:161], v[190:193], v[102:105]
	v_mfma_f32_16x16x32_bf16 v[92:95], v[150:153], v[206:209], v[92:95]
	v_mfma_f32_16x16x32_bf16 v[84:87], v[158:161], v[206:209], v[84:87]
	v_mfma_f32_16x16x32_bf16 v[76:79], v[150:153], v[214:217], v[76:79]
	v_mfma_f32_16x16x32_bf16 v[68:71], v[158:161], v[214:217], v[68:71]
	v_mfma_f32_16x16x32_bf16 v[126:129], v[154:157], v[186:189], v[126:129]
	v_mfma_f32_16x16x32_bf16 v[118:121], v[162:165], v[186:189], v[118:121]
	v_mfma_f32_16x16x32_bf16 v[110:113], v[154:157], v[202:205], v[110:113]
	v_mfma_f32_16x16x32_bf16 v[102:105], v[162:165], v[202:205], v[102:105]
	v_mfma_f32_16x16x32_bf16 v[92:95], v[154:157], v[210:213], v[92:95]
	v_mfma_f32_16x16x32_bf16 v[84:87], v[162:165], v[210:213], v[84:87]
	v_mfma_f32_16x16x32_bf16 v[76:79], v[154:157], v[218:221], v[76:79]
	v_mfma_f32_16x16x32_bf16 v[68:71], v[162:165], v[218:221], v[68:71]
	s_setprio 0
	s_setprio 1
	v_mfma_f32_16x16x32_bf16 v[122:125], v[166:169], v[182:185], v[122:125]
	v_mfma_f32_16x16x32_bf16 v[114:117], v[174:177], v[182:185], v[114:117]
	v_mfma_f32_16x16x32_bf16 v[106:109], v[166:169], v[190:193], v[106:109]
	v_mfma_f32_16x16x32_bf16 v[98:101], v[174:177], v[190:193], v[98:101]
	v_mfma_f32_16x16x32_bf16 v[88:91], v[166:169], v[206:209], v[88:91]
	v_mfma_f32_16x16x32_bf16 v[80:83], v[174:177], v[206:209], v[80:83]
	v_mfma_f32_16x16x32_bf16 v[72:75], v[166:169], v[214:217], v[72:75]
	v_mfma_f32_16x16x32_bf16 v[64:67], v[174:177], v[214:217], v[64:67]
	v_mfma_f32_16x16x32_bf16 v[122:125], v[170:173], v[186:189], v[122:125]
	v_mfma_f32_16x16x32_bf16 v[114:117], v[178:181], v[186:189], v[114:117]
	v_mfma_f32_16x16x32_bf16 v[106:109], v[170:173], v[202:205], v[106:109]
	v_mfma_f32_16x16x32_bf16 v[98:101], v[178:181], v[202:205], v[98:101]
	v_mfma_f32_16x16x32_bf16 v[88:91], v[170:173], v[210:213], v[88:91]
	v_mfma_f32_16x16x32_bf16 v[80:83], v[178:181], v[210:213], v[80:83]
	v_mfma_f32_16x16x32_bf16 v[72:75], v[170:173], v[218:221], v[72:75]
	v_mfma_f32_16x16x32_bf16 v[64:67], v[178:181], v[218:221], v[64:67]
	s_setprio 0
	s_barrier
	s_add_i32 s55, s55, s39
	v_lshl_add_u64 v[140:141], s[26:27], 0, v[96:97]
	s_mov_b32 m0, s55
	ds_read_b128 v[182:185], v148 offset:16384
	ds_read_b128 v[186:189], v148 offset:17408
	ds_read_b128 v[190:193], v148 offset:18432
	ds_read_b128 v[202:205], v148 offset:19456
	ds_read_b128 v[206:209], v148 offset:20480
	ds_read_b128 v[210:213], v148 offset:21504
	ds_read_b128 v[214:217], v148 offset:22528
	ds_read_b128 v[218:221], v148 offset:23552
	global_load_lds_dwordx4 v[140:141], off
	s_add_i32 m0, s55, 0x2000
	s_add_u32 s56, s26, 0x40000
	v_lshl_add_u64 v[194:195], s[26:27], 0, v[130:131]
	s_addc_u32 s57, s27, 0
	s_add_i32 s55, s60, s39
	global_load_lds_dwordx4 v[194:195], off
	v_lshl_add_u64 v[196:197], s[56:57], 0, v[96:97]
	s_mov_b32 m0, s55
	v_lshl_add_u64 v[198:199], s[28:29], 0, v[132:133]
	global_load_lds_dwordx4 v[196:197], off
	v_lshl_add_u64 v[196:197], s[56:57], 0, v[130:131]
	s_add_i32 m0, s55, 0x2000
	s_nop 0
	global_load_lds_dwordx4 v[196:197], off
	v_lshl_add_u64 v[196:197], s[28:29], 0, v[134:135]
	s_mov_b32 m0, s40
	s_nop 0
	global_load_lds_dwordx4 v[196:197], off
	s_mov_b32 m0, s41
	s_nop 0
	global_load_lds_dwordx4 v[198:199], off
	s_waitcnt lgkmcnt(0)
	s_barrier
	s_setprio 1
	s_waitcnt lgkmcnt(0)
	v_mfma_f32_16x16x32_bf16 v[60:63], v[150:153], v[182:185], v[60:63]
	v_mfma_f32_16x16x32_bf16 v[52:55], v[158:161], v[182:185], v[52:55]
	v_mfma_f32_16x16x32_bf16 v[44:47], v[150:153], v[190:193], v[44:47]
	v_mfma_f32_16x16x32_bf16 v[36:39], v[158:161], v[190:193], v[36:39]
	v_mfma_f32_16x16x32_bf16 v[28:31], v[150:153], v[206:209], v[28:31]
	v_mfma_f32_16x16x32_bf16 v[20:23], v[158:161], v[206:209], v[20:23]
	v_mfma_f32_16x16x32_bf16 v[12:15], v[150:153], v[214:217], v[12:15]
	v_mfma_f32_16x16x32_bf16 v[4:7], v[158:161], v[214:217], v[4:7]
	v_mfma_f32_16x16x32_bf16 v[60:63], v[154:157], v[186:189], v[60:63]
	v_mfma_f32_16x16x32_bf16 v[52:55], v[162:165], v[186:189], v[52:55]
	v_mfma_f32_16x16x32_bf16 v[44:47], v[154:157], v[202:205], v[44:47]
	v_mfma_f32_16x16x32_bf16 v[36:39], v[162:165], v[202:205], v[36:39]
	v_mfma_f32_16x16x32_bf16 v[28:31], v[154:157], v[210:213], v[28:31]
	v_mfma_f32_16x16x32_bf16 v[20:23], v[162:165], v[210:213], v[20:23]
	v_mfma_f32_16x16x32_bf16 v[12:15], v[154:157], v[218:221], v[12:15]
	v_mfma_f32_16x16x32_bf16 v[4:7], v[162:165], v[218:221], v[4:7]
	s_setprio 0
	s_setprio 1
	v_mfma_f32_16x16x32_bf16 v[56:59], v[166:169], v[182:185], v[56:59]
	v_mfma_f32_16x16x32_bf16 v[48:51], v[174:177], v[182:185], v[48:51]
	v_mfma_f32_16x16x32_bf16 v[40:43], v[166:169], v[190:193], v[40:43]
	v_mfma_f32_16x16x32_bf16 v[32:35], v[174:177], v[190:193], v[32:35]
	v_mfma_f32_16x16x32_bf16 v[24:27], v[166:169], v[206:209], v[24:27]
	v_mfma_f32_16x16x32_bf16 v[16:19], v[174:177], v[206:209], v[16:19]
	v_mfma_f32_16x16x32_bf16 v[8:11], v[166:169], v[214:217], v[8:11]
	v_mfma_f32_16x16x32_bf16 v[0:3], v[174:177], v[214:217], v[0:3]
	v_mfma_f32_16x16x32_bf16 v[56:59], v[170:173], v[186:189], v[56:59]
	v_mfma_f32_16x16x32_bf16 v[48:51], v[178:181], v[186:189], v[48:51]
	v_mfma_f32_16x16x32_bf16 v[40:43], v[170:173], v[202:205], v[40:43]
	v_mfma_f32_16x16x32_bf16 v[32:35], v[178:181], v[202:205], v[32:35]
	v_mfma_f32_16x16x32_bf16 v[24:27], v[170:173], v[210:213], v[24:27]
	v_mfma_f32_16x16x32_bf16 v[16:19], v[178:181], v[210:213], v[16:19]
	v_mfma_f32_16x16x32_bf16 v[8:11], v[170:173], v[218:221], v[8:11]
	v_mfma_f32_16x16x32_bf16 v[0:3], v[178:181], v[218:221], v[0:3]
	s_setprio 0
	s_barrier
	s_add_i32 s55, 0, 0x18000
	v_add_u32_e32 v149, s55, v143
	s_add_i32 s56, 0, 0x1c000
	ds_read_b128 v[150:153], v149
	ds_read_b128 v[154:157], v149 offset:1024
	ds_read_b128 v[158:161], v149 offset:2048
	ds_read_b128 v[162:165], v149 offset:3072
	v_add_u32_e32 v149, s56, v143
	ds_read_b128 v[166:169], v149
	ds_read_b128 v[170:173], v149 offset:1024
	ds_read_b128 v[174:177], v149 offset:2048
	ds_read_b128 v[178:181], v149 offset:3072
	s_add_u32 s28, s28, 0x40000
	s_addc_u32 s29, s29, 0
	s_mov_b32 m0, s42
	v_lshl_add_u64 v[200:201], s[28:29], 0, v[134:135]
	ds_read_b128 v[182:185], v148 offset:32768
	ds_read_b128 v[186:189], v148 offset:33792
	ds_read_b128 v[190:193], v148 offset:34816
	ds_read_b128 v[202:205], v148 offset:35840
	ds_read_b128 v[206:209], v148 offset:36864
	ds_read_b128 v[210:213], v148 offset:37888
	ds_read_b128 v[214:217], v148 offset:38912
	ds_read_b128 v[218:221], v148 offset:39936
	global_load_lds_dwordx4 v[200:201], off
	v_lshl_add_u64 v[200:201], s[28:29], 0, v[132:133]
	s_mov_b32 m0, s43
	s_nop 0
	global_load_lds_dwordx4 v[200:201], off
	s_waitcnt vmcnt(8)
	s_waitcnt lgkmcnt(0)
	s_barrier
	s_setprio 1
	s_waitcnt lgkmcnt(0)
	v_mfma_f32_16x16x32_bf16 v[126:129], v[150:153], v[182:185], v[126:129]
	v_mfma_f32_16x16x32_bf16 v[118:121], v[158:161], v[182:185], v[118:121]
	v_mfma_f32_16x16x32_bf16 v[110:113], v[150:153], v[190:193], v[110:113]
	v_mfma_f32_16x16x32_bf16 v[102:105], v[158:161], v[190:193], v[102:105]
	v_mfma_f32_16x16x32_bf16 v[92:95], v[150:153], v[206:209], v[92:95]
	v_mfma_f32_16x16x32_bf16 v[84:87], v[158:161], v[206:209], v[84:87]
	v_mfma_f32_16x16x32_bf16 v[76:79], v[150:153], v[214:217], v[76:79]
	v_mfma_f32_16x16x32_bf16 v[68:71], v[158:161], v[214:217], v[68:71]
	v_mfma_f32_16x16x32_bf16 v[126:129], v[154:157], v[186:189], v[126:129]
	v_mfma_f32_16x16x32_bf16 v[118:121], v[162:165], v[186:189], v[118:121]
	v_mfma_f32_16x16x32_bf16 v[110:113], v[154:157], v[202:205], v[110:113]
	v_mfma_f32_16x16x32_bf16 v[102:105], v[162:165], v[202:205], v[102:105]
	v_mfma_f32_16x16x32_bf16 v[92:95], v[154:157], v[210:213], v[92:95]
	v_mfma_f32_16x16x32_bf16 v[84:87], v[162:165], v[210:213], v[84:87]
	v_mfma_f32_16x16x32_bf16 v[76:79], v[154:157], v[218:221], v[76:79]
	v_mfma_f32_16x16x32_bf16 v[68:71], v[162:165], v[218:221], v[68:71]
	s_setprio 0
	s_setprio 1
	v_mfma_f32_16x16x32_bf16 v[122:125], v[166:169], v[182:185], v[122:125]
	v_mfma_f32_16x16x32_bf16 v[114:117], v[174:177], v[182:185], v[114:117]
	v_mfma_f32_16x16x32_bf16 v[106:109], v[166:169], v[190:193], v[106:109]
	v_mfma_f32_16x16x32_bf16 v[98:101], v[174:177], v[190:193], v[98:101]
	v_mfma_f32_16x16x32_bf16 v[88:91], v[166:169], v[206:209], v[88:91]
	v_mfma_f32_16x16x32_bf16 v[80:83], v[174:177], v[206:209], v[80:83]
	v_mfma_f32_16x16x32_bf16 v[72:75], v[166:169], v[214:217], v[72:75]
	v_mfma_f32_16x16x32_bf16 v[64:67], v[174:177], v[214:217], v[64:67]
	v_mfma_f32_16x16x32_bf16 v[122:125], v[170:173], v[186:189], v[122:125]
	v_mfma_f32_16x16x32_bf16 v[114:117], v[178:181], v[186:189], v[114:117]
	v_mfma_f32_16x16x32_bf16 v[106:109], v[170:173], v[202:205], v[106:109]
	v_mfma_f32_16x16x32_bf16 v[98:101], v[178:181], v[202:205], v[98:101]
	v_mfma_f32_16x16x32_bf16 v[88:91], v[170:173], v[210:213], v[88:91]
	v_mfma_f32_16x16x32_bf16 v[80:83], v[178:181], v[210:213], v[80:83]
	v_mfma_f32_16x16x32_bf16 v[72:75], v[170:173], v[218:221], v[72:75]
	v_mfma_f32_16x16x32_bf16 v[64:67], v[178:181], v[218:221], v[64:67]
	s_setprio 0
	s_barrier
	s_add_i32 s28, s55, s39
	v_lshl_add_u64 v[140:141], v[140:141], 0, s[64:65]
	s_mov_b32 m0, s28
	ds_read_b128 v[182:185], v148 offset:49152
	ds_read_b128 v[186:189], v148 offset:50176
	ds_read_b128 v[190:193], v148 offset:51200
	ds_read_b128 v[202:205], v148 offset:52224
	ds_read_b128 v[206:209], v148 offset:53248
	ds_read_b128 v[210:213], v148 offset:54272
	ds_read_b128 v[214:217], v148 offset:55296
	ds_read_b128 v[218:221], v148 offset:56320
	global_load_lds_dwordx4 v[140:141], off
	s_add_i32 m0, s28, 0x2000
	s_add_u32 s26, s26, 0x40080
	v_lshl_add_u64 v[140:141], v[194:195], 0, s[64:65]
	s_addc_u32 s27, s27, 0
	s_add_i32 s28, s56, s39
	global_load_lds_dwordx4 v[140:141], off
	v_lshl_add_u64 v[140:141], s[26:27], 0, v[96:97]
	s_mov_b32 m0, s28
	s_nop 0
	global_load_lds_dwordx4 v[140:141], off
	v_lshl_add_u64 v[140:141], s[26:27], 0, v[130:131]
	s_add_i32 m0, s28, 0x2000
	s_nop 0
	global_load_lds_dwordx4 v[140:141], off
	v_lshl_add_u64 v[140:141], v[196:197], 0, s[64:65]
	s_mov_b32 m0, s44
	s_nop 0
	global_load_lds_dwordx4 v[140:141], off
	v_lshl_add_u64 v[140:141], v[198:199], 0, s[64:65]
	s_mov_b32 m0, s45
	s_nop 0
	global_load_lds_dwordx4 v[140:141], off
	s_waitcnt vmcnt(8)
	s_waitcnt lgkmcnt(0)
	s_barrier
	s_setprio 1
	s_waitcnt lgkmcnt(0)
	v_mfma_f32_16x16x32_bf16 v[60:63], v[150:153], v[182:185], v[60:63]
	v_mfma_f32_16x16x32_bf16 v[52:55], v[158:161], v[182:185], v[52:55]
	v_mfma_f32_16x16x32_bf16 v[44:47], v[150:153], v[190:193], v[44:47]
	v_mfma_f32_16x16x32_bf16 v[36:39], v[158:161], v[190:193], v[36:39]
	v_mfma_f32_16x16x32_bf16 v[28:31], v[150:153], v[206:209], v[28:31]
	v_mfma_f32_16x16x32_bf16 v[20:23], v[158:161], v[206:209], v[20:23]
	v_mfma_f32_16x16x32_bf16 v[12:15], v[150:153], v[214:217], v[12:15]
	v_mfma_f32_16x16x32_bf16 v[4:7], v[158:161], v[214:217], v[4:7]
	v_mfma_f32_16x16x32_bf16 v[60:63], v[154:157], v[186:189], v[60:63]
	v_mfma_f32_16x16x32_bf16 v[52:55], v[162:165], v[186:189], v[52:55]
	v_mfma_f32_16x16x32_bf16 v[44:47], v[154:157], v[202:205], v[44:47]
	v_mfma_f32_16x16x32_bf16 v[36:39], v[162:165], v[202:205], v[36:39]
	v_mfma_f32_16x16x32_bf16 v[28:31], v[154:157], v[210:213], v[28:31]
	v_mfma_f32_16x16x32_bf16 v[20:23], v[162:165], v[210:213], v[20:23]
	v_mfma_f32_16x16x32_bf16 v[12:15], v[154:157], v[218:221], v[12:15]
	v_mfma_f32_16x16x32_bf16 v[4:7], v[162:165], v[218:221], v[4:7]
	s_setprio 0
	s_setprio 1
	v_mfma_f32_16x16x32_bf16 v[56:59], v[166:169], v[182:185], v[56:59]
	v_mfma_f32_16x16x32_bf16 v[48:51], v[174:177], v[182:185], v[48:51]
	v_mfma_f32_16x16x32_bf16 v[40:43], v[166:169], v[190:193], v[40:43]
	v_mfma_f32_16x16x32_bf16 v[32:35], v[174:177], v[190:193], v[32:35]
	v_mfma_f32_16x16x32_bf16 v[24:27], v[166:169], v[206:209], v[24:27]
	v_mfma_f32_16x16x32_bf16 v[16:19], v[174:177], v[206:209], v[16:19]
	v_mfma_f32_16x16x32_bf16 v[8:11], v[166:169], v[214:217], v[8:11]
	v_mfma_f32_16x16x32_bf16 v[0:3], v[174:177], v[214:217], v[0:3]
	v_mfma_f32_16x16x32_bf16 v[56:59], v[170:173], v[186:189], v[56:59]
	v_mfma_f32_16x16x32_bf16 v[48:51], v[178:181], v[186:189], v[48:51]
	v_mfma_f32_16x16x32_bf16 v[40:43], v[170:173], v[202:205], v[40:43]
	v_mfma_f32_16x16x32_bf16 v[32:35], v[178:181], v[202:205], v[32:35]
	v_mfma_f32_16x16x32_bf16 v[24:27], v[170:173], v[210:213], v[24:27]
	v_mfma_f32_16x16x32_bf16 v[16:19], v[178:181], v[210:213], v[16:19]
	v_mfma_f32_16x16x32_bf16 v[8:11], v[170:173], v[218:221], v[8:11]
	v_mfma_f32_16x16x32_bf16 v[0:3], v[178:181], v[218:221], v[0:3]
	s_setprio 0
	s_barrier
	s_add_i32 s54, s54, 2
	s_add_u32 s24, s24, 0x100
	s_addc_u32 s25, s25, 0
	s_add_u32 s52, s52, 0x100
	s_addc_u32 s53, s53, 0
	s_cmp_gt_u32 s54, 13
	s_cbranch_scc1 .Lgu_kdone

.LBB0_149:
	s_bitcmp1_b32 s47, 0
	s_cselect_b64 s[24:25], -1, 0
	s_and_b64 vcc, exec, s[24:25]
	s_cbranch_vccnz .LBB0_151
	s_waitcnt vmcnt(16)
	v_mov_b64_e32 v[150:151], v[226:227]
	v_mov_b64_e32 v[152:153], v[228:229]
	v_mov_b64_e32 v[154:155], v[230:231]
	v_mov_b64_e32 v[156:157], v[232:233]
	v_mov_b64_e32 v[158:159], v[234:235]
	v_mov_b64_e32 v[160:161], v[236:237]
	v_mov_b64_e32 v[162:163], v[238:239]
	v_mov_b64_e32 v[164:165], v[240:241]
	v_add_f32_e32 v154, v154, v155
	v_add_f32_e32 v156, v156, v157
	v_mov_b32_e32 v140, v163
	v_mov_b32_e32 v141, v164
	v_mov_b32_e32 v163, v165
	v_pk_add_f32 v[140:141], v[140:141], v[162:163]
	v_mov_b32_e32 v162, v159
	v_mov_b32_e32 v163, v160
	v_mov_b32_e32 v159, v161
	v_pk_add_f32 v[158:159], v[162:163], v[158:159]
	v_pk_add_f32 v[140:141], v[140:141], v[140:141] op_sel:[0,1] op_sel_hi:[1,0]
	v_pk_add_f32 v[158:159], v[158:159], v[158:159] op_sel:[0,1] op_sel_hi:[1,0]
	v_mov_b32_e32 v141, v150
	v_mov_b32_e32 v159, v151
	v_mov_b32_e32 v155, v152
	v_mov_b32_e32 v157, v153
	v_pk_add_f32 v[140:141], v[140:141], v[158:159]
	v_pk_add_f32 v[150:151], v[154:155], v[156:157]
	s_nop 0
	v_pk_add_f32 v[140:141], v[140:141], v[150:151]
	s_nop 0
	v_add_f32_e32 v140, v140, v141
	v_fmamk_f32 v140, v140, 0x3a800000, v249
	v_rsq_f32_e32 v140, v140
	ds_write_b32 v147, v140
	s_waitcnt lgkmcnt(0)
	s_barrier
